# v12: v9 + GLA group-combine loops software-pipelined (next rows loaded before current stores)
# speedup vs baseline: 1.0049x; 1.0049x over previous
; __device__ __forceinline__ float sigmoidf_(float x) { return __builtin_amdgcn_rcpf(1.0f + __builtin_amdgcn_exp2f(x * -1.4426950408889634f)); }
; __device__ __forceinline__ void gla_group_combine(const Frame& F, int l, bool last, int b, int h, int role, int nroles, unsigned* gwd, bool arrive) {
;     ...
;     for (int r4 = (role * 8 + w) * 4; r4 < nrow; r4 += nroles * 32) {
;         const int rl = r4 + (lane >> 4);
;         const int row = (rl < SEQ) ? b * SEQ + rl : TL + b * CTXL + (rl - SEQ);
;         const size_t o = (size_t)row * DM + h * 256 + (lane & 15) * 16;
;         const f16x8 a0 = *(const f16x8*)(F.H16 + o), a1 = *(const f16x8*)(F.H16 + o + 8), b0 = *(const f16x8*)(F.OB + o), b1 = *(const f16x8*)(F.OB + o + 8);
;         f16* gp = F.Z + (size_t)row * ZLD + Z_GR + h * 256 + (lane & 15) * 16;
;         const f16x8 r0 = *(const f16x8*)gp, r1 = *(const f16x8*)(gp + 8);
;         float v[16], r[16]; float ss = 0.f;
; #pragma unroll
;         for (int e = 0; e < 8; ++e) { v[e] = (float)a0[e] + (float)b0[e]; v[8 + e] = (float)a1[e] + (float)b1[e]; r[e] = (float)r0[e]; r[8 + e] = (float)r1[e]; }
; #pragma unroll
;         for (int e = 0; e < 16; ++e) ss += v[e] * v[e];
;         ss += __shfl_xor(ss, 1); ss += __shfl_xor(ss, 2); ss += __shfl_xor(ss, 4); ss += __shfl_xor(ss, 8);
;         const float rstd = rsqrtf(ss * (1.0f / 256.0f) + 1e-6f);
;         float y[16];
; #pragma unroll
;         for (int e = 0; e < 16; ++e) y[e] = v[e] * rstd * wv[e] * r[e] * sigmoidf_(r[e]);
;         u32x4 w0, w1; w0.x = pk_f16(y[0], y[1]); w0.y = pk_f16(y[2], y[3]); w0.z = pk_f16(y[4], y[5]); w0.w = pk_f16(y[6], y[7]);
;         w1.x = pk_f16(y[8], y[9]); w1.y = pk_f16(y[10], y[11]); w1.z = pk_f16(y[12], y[13]); w1.w = pk_f16(y[14], y[15]);
;         *(u32x4*)gp = w0; *(u32x4*)(gp + 8) = w1;
.LBB0_633:
	v_add_u32_e32 v22, s2, v24
	v_mov_b32_e32 v23, s3
	v_mov_b32_e32 v29, s4
	v_cmp_gt_i32_e32 vcc, s36, v22
	v_mov_b64_e32 v[20:21], s[22:23]
	s_addk_i32 s2, 0x100
	v_cndmask_b32_e32 v23, v23, v29, vcc
	v_add_u32_e32 v22, v22, v23
	v_ashrrev_i32_e32 v23, 31, v22
	v_mad_i64_i32 v[20:21], s[6:7], v22, s14, v[20:21]
	v_lshlrev_b64 v[22:23], 10, v[22:23]
	v_lshl_add_u64 v[20:21], s[8:9], 1, v[20:21]
	v_lshl_add_u64 v[22:23], v[22:23], 0, v[18:19]
	v_lshl_add_u64 v[30:31], v[20:21], 0, v[0:1]
	v_lshlrev_b64 v[38:39], 1, v[22:23]
	v_lshl_add_u64 v[20:21], v[30:31], 0, s[28:29]
	v_add_co_u32_e32 v22, vcc, s36, v30
	v_lshl_add_u64 v[46:47], s[52:53], 0, v[38:39]
	v_lshl_add_u64 v[50:51], s[54:55], 0, v[38:39]
	v_addc_co_u32_e32 v23, vcc, 0, v31, vcc
	global_load_dwordx4 v[30:33], v[20:21], off offset:16
	global_load_dwordx4 v[34:37], v[22:23], off offset:3072
	global_load_dwordx4 v[38:41], v[46:47], off offset:16
	global_load_dwordx4 v[42:45], v[50:51], off offset:16
	s_nop 0
	global_load_dwordx4 v[46:49], v[46:47], off
	s_nop 0
	global_load_dwordx4 v[50:53], v[50:51], off
	s_cmp_lt_i32 s2, s0
	s_waitcnt vmcnt(0)
.Lcomb_a_loop:
	s_waitcnt vmcnt(2)
	v_cvt_f32_f16_e32 v66, v40
	v_cvt_f32_f16_e32 v54, v33
	v_cvt_f32_f16_sdwa v55, v33 dst_sel:DWORD dst_unused:UNUSED_PAD src0_sel:WORD_1
	v_cvt_f32_f16_e32 v56, v32
	v_cvt_f32_f16_sdwa v57, v32 dst_sel:DWORD dst_unused:UNUSED_PAD src0_sel:WORD_1
	v_cvt_f32_f16_e32 v32, v31
	v_cvt_f32_f16_sdwa v33, v31 dst_sel:DWORD dst_unused:UNUSED_PAD src0_sel:WORD_1
	v_cvt_f32_f16_e32 v58, v30
	v_cvt_f32_f16_sdwa v59, v30 dst_sel:DWORD dst_unused:UNUSED_PAD src0_sel:WORD_1
	v_cvt_f32_f16_e32 v30, v37
	v_cvt_f32_f16_sdwa v31, v37 dst_sel:DWORD dst_unused:UNUSED_PAD src0_sel:WORD_1
	v_cvt_f32_f16_e32 v60, v36
	v_cvt_f32_f16_sdwa v61, v36 dst_sel:DWORD dst_unused:UNUSED_PAD src0_sel:WORD_1
	v_cvt_f32_f16_e32 v36, v35
	v_cvt_f32_f16_sdwa v37, v35 dst_sel:DWORD dst_unused:UNUSED_PAD src0_sel:WORD_1
	v_cvt_f32_f16_e32 v62, v34
	v_cvt_f32_f16_sdwa v63, v34 dst_sel:DWORD dst_unused:UNUSED_PAD src0_sel:WORD_1
	v_cvt_f32_f16_e32 v34, v41
	v_cvt_f32_f16_sdwa v35, v41 dst_sel:DWORD dst_unused:UNUSED_PAD src0_sel:WORD_1
	v_cvt_f32_f16_e32 v64, v45
	v_cvt_f32_f16_sdwa v65, v45 dst_sel:DWORD dst_unused:UNUSED_PAD src0_sel:WORD_1
	v_cvt_f32_f16_sdwa v67, v40 dst_sel:DWORD dst_unused:UNUSED_PAD src0_sel:WORD_1
	v_cvt_f32_f16_e32 v40, v44
	v_cvt_f32_f16_sdwa v41, v44 dst_sel:DWORD dst_unused:UNUSED_PAD src0_sel:WORD_1
	v_cvt_f32_f16_e32 v44, v39
	v_cvt_f32_f16_sdwa v45, v39 dst_sel:DWORD dst_unused:UNUSED_PAD src0_sel:WORD_1
	v_cvt_f32_f16_e32 v68, v43
	v_cvt_f32_f16_sdwa v69, v43 dst_sel:DWORD dst_unused:UNUSED_PAD src0_sel:WORD_1
	v_cvt_f32_f16_e32 v70, v38
	v_cvt_f32_f16_sdwa v71, v38 dst_sel:DWORD dst_unused:UNUSED_PAD src0_sel:WORD_1
	v_cvt_f32_f16_e32 v38, v42
	v_cvt_f32_f16_sdwa v39, v42 dst_sel:DWORD dst_unused:UNUSED_PAD src0_sel:WORD_1
	v_cvt_f32_f16_e32 v42, v49
	v_cvt_f32_f16_sdwa v43, v49 dst_sel:DWORD dst_unused:UNUSED_PAD src0_sel:WORD_1
	v_cvt_f32_f16_e32 v72, v53
	v_cvt_f32_f16_sdwa v73, v53 dst_sel:DWORD dst_unused:UNUSED_PAD src0_sel:WORD_1
	v_cvt_f32_f16_e32 v74, v48
	v_cvt_f32_f16_sdwa v75, v48 dst_sel:DWORD dst_unused:UNUSED_PAD src0_sel:WORD_1
	v_cvt_f32_f16_e32 v48, v52
	v_cvt_f32_f16_sdwa v49, v52 dst_sel:DWORD dst_unused:UNUSED_PAD src0_sel:WORD_1
	v_cvt_f32_f16_e32 v52, v47
	v_cvt_f32_f16_sdwa v53, v47 dst_sel:DWORD dst_unused:UNUSED_PAD src0_sel:WORD_1
	v_cvt_f32_f16_e32 v78, v46
	v_cvt_f32_f16_sdwa v79, v46 dst_sel:DWORD dst_unused:UNUSED_PAD src0_sel:WORD_1
	v_cvt_f32_f16_e32 v46, v50
	v_cvt_f32_f16_sdwa v47, v50 dst_sel:DWORD dst_unused:UNUSED_PAD src0_sel:WORD_1
	v_cvt_f32_f16_e32 v76, v51
	v_cvt_f32_f16_sdwa v77, v51 dst_sel:DWORD dst_unused:UNUSED_PAD src0_sel:WORD_1
	v_mul_f32_e32 v29, 0xbfb8aa3b, v54
	v_mul_f32_e32 v50, 0xbfb8aa3b, v55
	v_mul_f32_e32 v51, 0xbfb8aa3b, v56
	v_exp_f32_e32 v29, v29
	v_exp_f32_e32 v93, v50
	v_pk_add_f32 v[46:47], v[78:79], v[46:47]
	v_exp_f32_e32 v94, v51
	v_pk_add_f32 v[50:51], v[52:53], v[76:77]
	v_pk_mul_f32 v[76:77], v[46:47], v[46:47]
	v_pk_add_f32 v[48:49], v[74:75], v[48:49]
	v_pk_mul_f32 v[74:75], v[50:51], v[50:51]
	v_add_f32_e32 v76, v76, v77
	v_add_f32_e32 v74, v74, v76
	v_pk_add_f32 v[42:43], v[42:43], v[72:73]
	v_pk_mul_f32 v[72:73], v[48:49], v[48:49]
	v_add_f32_e32 v29, 1.0, v29
	v_add_f32_e32 v76, 1.0, v93
	v_add_f32_e32 v93, v75, v74
	v_rcp_f32_e32 v74, v29
	v_add_f32_e32 v29, v72, v93
	v_pk_add_f32 v[38:39], v[70:71], v[38:39]
	v_pk_mul_f32 v[70:71], v[42:43], v[42:43]
	v_add_f32_e32 v29, v73, v29
	v_add_f32_e32 v29, v70, v29
	v_pk_add_f32 v[44:45], v[44:45], v[68:69]
	v_pk_mul_f32 v[68:69], v[38:39], v[38:39]
	v_add_f32_e32 v29, v71, v29
	v_add_f32_e32 v29, v68, v29
	v_pk_add_f32 v[40:41], v[66:67], v[40:41]
	v_pk_mul_f32 v[66:67], v[44:45], v[44:45]
	v_add_f32_e32 v29, v69, v29
	v_add_f32_e32 v29, v66, v29
	v_pk_add_f32 v[34:35], v[34:35], v[64:65]
	v_pk_mul_f32 v[64:65], v[40:41], v[40:41]
	v_add_f32_e32 v29, v67, v29
	v_add_f32_e32 v29, v64, v29
	v_pk_mul_f32 v[52:53], v[34:35], v[34:35]
	v_add_f32_e32 v29, v65, v29
	v_add_f32_e32 v29, v52, v29
	v_add_f32_e32 v29, v53, v29
	ds_bpermute_b32 v52, v25, v29
	v_mul_f32_e32 v80, 0xbfb8aa3b, v57
	v_mul_f32_e32 v81, 0xbfb8aa3b, v32
	v_mul_f32_e32 v82, 0xbfb8aa3b, v33
	v_mul_f32_e32 v83, 0xbfb8aa3b, v58
	s_waitcnt lgkmcnt(0)
; __device__ __forceinline__ float sigmoidf_(float x) { return __builtin_amdgcn_rcpf(1.0f + __builtin_amdgcn_exp2f(x * -1.4426950408889634f)); }
; __device__ __forceinline__ void gla_group_combine(const Frame& F, int l, bool last, int b, int h, int role, int nroles, unsigned* gwd, bool arrive) {
;     ...
;         float v[16], r[16]; float ss = 0.f;
; #pragma unroll
;         for (int e = 0; e < 8; ++e) { v[e] = (float)a0[e] + (float)b0[e]; v[8 + e] = (float)a1[e] + (float)b1[e]; r[e] = (float)r0[e]; r[8 + e] = (float)r1[e]; }
; #pragma unroll
;         for (int e = 0; e < 16; ++e) ss += v[e] * v[e];
;         ss += __shfl_xor(ss, 1); ss += __shfl_xor(ss, 2); ss += __shfl_xor(ss, 4); ss += __shfl_xor(ss, 8);
;         const float rstd = rsqrtf(ss * (1.0f / 256.0f) + 1e-6f);
;         float y[16];
; #pragma unroll
;         for (int e = 0; e < 16; ++e) y[e] = v[e] * rstd * wv[e] * r[e] * sigmoidf_(r[e]);
;         u32x4 w0, w1; w0.x = pk_f16(y[0], y[1]); w0.y = pk_f16(y[2], y[3]); w0.z = pk_f16(y[4], y[5]); w0.w = pk_f16(y[6], y[7]);
;         w1.x = pk_f16(y[8], y[9]); w1.y = pk_f16(y[10], y[11]); w1.z = pk_f16(y[12], y[13]); w1.w = pk_f16(y[14], y[15]);
;         *(u32x4*)gp = w0; *(u32x4*)(gp + 8) = w1;
	v_add_f32_e32 v29, v29, v52
	ds_bpermute_b32 v52, v26, v29
	v_mul_f32_e32 v84, 0xbfb8aa3b, v59
	v_mul_f32_e32 v85, 0xbfb8aa3b, v30
	v_mul_f32_e32 v86, 0xbfb8aa3b, v31
	v_mul_f32_e32 v87, 0xbfb8aa3b, v60
	s_waitcnt lgkmcnt(0)
	v_add_f32_e32 v29, v29, v52
	ds_bpermute_b32 v52, v27, v29
	v_mul_f32_e32 v88, 0xbfb8aa3b, v61
	v_mul_f32_e32 v89, 0xbfb8aa3b, v36
	v_mul_f32_e32 v90, 0xbfb8aa3b, v37
	v_mul_f32_e32 v91, 0xbfb8aa3b, v62
	s_waitcnt lgkmcnt(0)
	v_add_f32_e32 v29, v29, v52
	ds_bpermute_b32 v52, v28, v29
	v_mul_f32_e32 v92, 0xbfb8aa3b, v63
	v_exp_f32_e32 v80, v80
	v_exp_f32_e32 v81, v81
	v_exp_f32_e32 v82, v82
	s_waitcnt lgkmcnt(0)
	v_add_f32_e32 v29, v29, v52
	v_fmamk_f32 v29, v29, 0x3b800000, v235
	v_mul_f32_e32 v52, 0x4b800000, v29
	v_cmp_gt_f32_e32 vcc, s88, v29
	v_exp_f32_e32 v83, v83
	v_exp_f32_e32 v84, v84
	v_cndmask_b32_e32 v29, v29, v52, vcc
	v_exp_f32_e32 v85, v85
	v_exp_f32_e32 v86, v86
	v_exp_f32_e32 v87, v87
	v_exp_f32_e32 v88, v88
	v_exp_f32_e32 v89, v89
	v_exp_f32_e32 v90, v90
	v_exp_f32_e32 v78, v91
	v_exp_f32_e32 v79, v92
	v_rsq_f32_e32 v29, v29
	v_add_f32_e32 v77, 1.0, v94
	v_add_f32_e32 v80, 1.0, v80
	v_add_f32_e32 v81, 1.0, v81
	v_add_f32_e32 v82, 1.0, v82
	v_add_f32_e32 v83, 1.0, v83
	v_add_f32_e32 v84, 1.0, v84
	v_add_f32_e32 v85, 1.0, v85
	v_add_f32_e32 v86, 1.0, v86
	v_add_f32_e32 v87, 1.0, v87
	v_add_f32_e32 v88, 1.0, v88
	v_add_f32_e32 v89, 1.0, v89
	v_add_f32_e32 v90, 1.0, v90
	v_add_f32_e32 v91, 1.0, v78
	v_add_f32_e32 v92, 1.0, v79
	v_mul_f32_e32 v52, 0x45800000, v29
	v_rcp_f32_e32 v75, v76
	v_rcp_f32_e32 v76, v77
	v_rcp_f32_e32 v77, v80
	v_rcp_f32_e32 v78, v81
	v_rcp_f32_e32 v79, v82
	v_rcp_f32_e32 v80, v83
	v_rcp_f32_e32 v81, v84
	v_rcp_f32_e32 v82, v85
	v_rcp_f32_e32 v83, v86
	v_rcp_f32_e32 v84, v87
	v_rcp_f32_e32 v85, v88
	v_rcp_f32_e32 v86, v89
	v_rcp_f32_e32 v87, v90
	v_rcp_f32_e32 v88, v91
	v_rcp_f32_e32 v89, v92
	v_cndmask_b32_e32 v52, v29, v52, vcc
	v_pk_mul_f32 v[46:47], v[46:47], v[52:53] op_sel_hi:[1,0]
	v_pk_mul_f32 v[50:51], v[50:51], v[52:53] op_sel_hi:[1,0]
	v_pk_mul_f32 v[48:49], v[48:49], v[52:53] op_sel_hi:[1,0]
	v_pk_mul_f32 v[42:43], v[42:43], v[52:53] op_sel_hi:[1,0]
	v_pk_mul_f32 v[38:39], v[38:39], v[52:53] op_sel_hi:[1,0]
	v_pk_mul_f32 v[44:45], v[44:45], v[52:53] op_sel_hi:[1,0]
	v_pk_mul_f32 v[40:41], v[40:41], v[52:53] op_sel_hi:[1,0]
	v_pk_mul_f32 v[34:35], v[34:35], v[52:53] op_sel_hi:[1,0]
	v_pk_mul_f32 v[46:47], v[14:15], v[46:47]
	v_pk_mul_f32 v[50:51], v[16:17], v[50:51]
	v_pk_mul_f32 v[48:49], v[10:11], v[48:49]
	v_pk_mul_f32 v[42:43], v[12:13], v[42:43]
	v_pk_mul_f32 v[38:39], v[6:7], v[38:39]
	v_pk_mul_f32 v[44:45], v[8:9], v[44:45]
	v_pk_mul_f32 v[40:41], v[2:3], v[40:41]
	v_pk_mul_f32 v[34:35], v[4:5], v[34:35]
	v_pk_mul_f32 v[46:47], v[46:47], v[62:63]
	v_pk_mul_f32 v[36:37], v[50:51], v[36:37]
	v_pk_mul_f32 v[48:49], v[48:49], v[60:61]
	v_pk_mul_f32 v[30:31], v[42:43], v[30:31]
	v_pk_mul_f32 v[38:39], v[38:39], v[58:59]
	v_pk_mul_f32 v[32:33], v[44:45], v[32:33]
	v_pk_mul_f32 v[40:41], v[40:41], v[56:57]
	v_pk_mul_f32 v[34:35], v[34:35], v[54:55]
	v_pk_mul_f32 v[42:43], v[88:89], v[46:47]
	v_pk_mul_f32 v[36:37], v[86:87], v[36:37]
	v_pk_mul_f32 v[44:45], v[84:85], v[48:49]
	v_pk_mul_f32 v[46:47], v[82:83], v[30:31]
	v_pk_mul_f32 v[38:39], v[80:81], v[38:39]
	v_pk_mul_f32 v[48:49], v[78:79], v[32:33]
	v_pk_mul_f32 v[40:41], v[76:77], v[40:41]
	v_pk_mul_f32 v[50:51], v[74:75], v[34:35]
	v_cvt_pk_f16_f32 v100, v42, v43
	v_cvt_pk_f16_f32 v101, v36, v37
	v_cvt_pk_f16_f32 v102, v44, v45
	v_cvt_pk_f16_f32 v103, v46, v47
	v_cvt_pk_f16_f32 v104, v38, v39
	v_cvt_pk_f16_f32 v105, v48, v49
	v_cvt_pk_f16_f32 v106, v40, v41
	v_cvt_pk_f16_f32 v107, v50, v51
	v_mov_b64_e32 v[108:109], v[20:21]
	v_mov_b64_e32 v[110:111], v[22:23]
	s_cbranch_scc0 .Lcomb_a_last
	v_add_u32_e32 v22, s2, v24
	v_mov_b32_e32 v23, s3
	v_mov_b32_e32 v29, s4
	v_cmp_gt_i32_e32 vcc, s36, v22
	v_mov_b64_e32 v[20:21], s[22:23]
	s_addk_i32 s2, 0x100
	v_cndmask_b32_e32 v23, v23, v29, vcc
	v_add_u32_e32 v22, v22, v23
	v_ashrrev_i32_e32 v23, 31, v22
	v_mad_i64_i32 v[20:21], s[6:7], v22, s14, v[20:21]
	v_lshlrev_b64 v[22:23], 10, v[22:23]
	v_lshl_add_u64 v[20:21], s[8:9], 1, v[20:21]
	v_lshl_add_u64 v[22:23], v[22:23], 0, v[18:19]
	v_lshl_add_u64 v[30:31], v[20:21], 0, v[0:1]
	v_lshlrev_b64 v[38:39], 1, v[22:23]
	v_lshl_add_u64 v[20:21], v[30:31], 0, s[28:29]
	v_add_co_u32_e32 v22, vcc, s36, v30
	v_lshl_add_u64 v[46:47], s[52:53], 0, v[38:39]
	v_lshl_add_u64 v[50:51], s[54:55], 0, v[38:39]
	v_addc_co_u32_e32 v23, vcc, 0, v31, vcc
	global_load_dwordx4 v[30:33], v[20:21], off offset:16
	global_load_dwordx4 v[34:37], v[22:23], off offset:3072
	global_load_dwordx4 v[38:41], v[46:47], off offset:16
	global_load_dwordx4 v[42:45], v[50:51], off offset:16
	s_nop 0
	global_load_dwordx4 v[46:49], v[46:47], off
	s_nop 0
	global_load_dwordx4 v[50:53], v[50:51], off
	s_cmp_lt_i32 s2, s0
	global_store_dwordx4 v[110:111], v[100:103], off offset:3072
	global_store_dwordx4 v[108:109], v[104:107], off offset:16
	s_branch .Lcomb_a_loop
.Lcomb_a_last:
	global_store_dwordx4 v[110:111], v[100:103], off offset:3072
	global_store_dwordx4 v[108:109], v[104:107], off offset:16

; __device__ __forceinline__ void gla_group_combine(const Frame& F, int l, bool last, int b, int h, int role, int nroles, unsigned* gwd, bool arrive) {
;     ...
; #pragma unroll 2
;     for (int r4 = (role * 8 + w) * 4; r4 < nrow; r4 += nroles * 32) {
;         const int rl = r4 + (lane >> 4);
;         const int row = (rl < SEQ) ? b * SEQ + rl : TL + b * CTXL + (rl - SEQ);
;         const size_t o = (size_t)row * DM + h * 256 + (lane & 15) * 16;
;         const f16x8 a0 = *(const f16x8*)(F.H16 + o), a1 = *(const f16x8*)(F.H16 + o + 8), b0 = *(const f16x8*)(F.OB + o), b1 = *(const f16x8*)(F.OB + o + 8);
;         f16* gp = F.Z + (size_t)row * ZLD + Z_GR + h * 256 + (lane & 15) * 16;
;         const f16x8 r0 = *(const f16x8*)gp, r1 = *(const f16x8*)(gp + 8);
;         float v[16], r[16]; float ss = 0.f;
; #pragma unroll
;         for (int e = 0; e < 8; ++e) { v[e] = (float)a0[e] + (float)b0[e]; v[8 + e] = (float)a1[e] + (float)b1[e]; r[e] = (float)r0[e]; r[8 + e] = (float)r1[e]; }
; #pragma unroll
;         for (int e = 0; e < 16; ++e) ss += v[e] * v[e];
;         ss += __shfl_xor(ss, 1); ss += __shfl_xor(ss, 2); ss += __shfl_xor(ss, 4); ss += __shfl_xor(ss, 8);
.LBB0_680:
	v_add_u32_e32 v22, s0, v133
	v_mov_b32_e32 v23, s1
	v_mov_b32_e32 v28, s6
	v_cmp_gt_i32_e32 vcc, s36, v22
	v_mov_b64_e32 v[20:21], s[22:23]
	s_addk_i32 s0, 0x100
	v_cndmask_b32_e32 v23, v23, v28, vcc
	v_add_u32_e32 v22, v22, v23
	v_ashrrev_i32_e32 v23, 31, v22
	v_mad_i64_i32 v[20:21], s[2:3], v22, s14, v[20:21]
	v_lshlrev_b64 v[22:23], 10, v[22:23]
	v_lshl_add_u64 v[20:21], s[30:31], 1, v[20:21]
	v_lshl_add_u64 v[22:23], v[22:23], 0, v[18:19]
	v_lshl_add_u64 v[28:29], v[20:21], 0, v[0:1]
	v_lshlrev_b64 v[36:37], 1, v[22:23]
	v_lshl_add_u64 v[20:21], v[28:29], 0, s[34:35]
	v_add_co_u32_e32 v22, vcc, s36, v28
	v_lshl_add_u64 v[44:45], s[52:53], 0, v[36:37]
	v_lshl_add_u64 v[48:49], s[54:55], 0, v[36:37]
	v_addc_co_u32_e32 v23, vcc, 0, v29, vcc
	global_load_dwordx4 v[28:31], v[20:21], off offset:16
	global_load_dwordx4 v[32:35], v[22:23], off offset:3072
	global_load_dwordx4 v[36:39], v[44:45], off offset:16
	global_load_dwordx4 v[40:43], v[48:49], off offset:16
	s_nop 0
	global_load_dwordx4 v[44:47], v[44:45], off
	s_nop 0
	global_load_dwordx4 v[48:51], v[48:49], off
	s_cmp_lt_i32 s0, s38
	s_waitcnt vmcnt(0)
.Lcomb_g_loop:
	s_waitcnt vmcnt(2)
	v_cvt_f32_f16_e32 v64, v38
	v_cvt_f32_f16_e32 v52, v31
	v_cvt_f32_f16_sdwa v53, v31 dst_sel:DWORD dst_unused:UNUSED_PAD src0_sel:WORD_1
	v_cvt_f32_f16_e32 v54, v30
	v_cvt_f32_f16_sdwa v55, v30 dst_sel:DWORD dst_unused:UNUSED_PAD src0_sel:WORD_1
	v_cvt_f32_f16_e32 v30, v29
	v_cvt_f32_f16_sdwa v31, v29 dst_sel:DWORD dst_unused:UNUSED_PAD src0_sel:WORD_1
	v_cvt_f32_f16_e32 v56, v28
	v_cvt_f32_f16_sdwa v57, v28 dst_sel:DWORD dst_unused:UNUSED_PAD src0_sel:WORD_1
	v_cvt_f32_f16_e32 v28, v35
	v_cvt_f32_f16_sdwa v29, v35 dst_sel:DWORD dst_unused:UNUSED_PAD src0_sel:WORD_1
	v_cvt_f32_f16_e32 v58, v34
	v_cvt_f32_f16_sdwa v59, v34 dst_sel:DWORD dst_unused:UNUSED_PAD src0_sel:WORD_1
	v_cvt_f32_f16_e32 v34, v33
	v_cvt_f32_f16_sdwa v35, v33 dst_sel:DWORD dst_unused:UNUSED_PAD src0_sel:WORD_1
	v_cvt_f32_f16_e32 v60, v32
	v_cvt_f32_f16_sdwa v61, v32 dst_sel:DWORD dst_unused:UNUSED_PAD src0_sel:WORD_1
	v_cvt_f32_f16_e32 v32, v39
	v_cvt_f32_f16_sdwa v33, v39 dst_sel:DWORD dst_unused:UNUSED_PAD src0_sel:WORD_1
	v_cvt_f32_f16_e32 v62, v43
	v_cvt_f32_f16_sdwa v63, v43 dst_sel:DWORD dst_unused:UNUSED_PAD src0_sel:WORD_1
	v_cvt_f32_f16_sdwa v65, v38 dst_sel:DWORD dst_unused:UNUSED_PAD src0_sel:WORD_1
	v_cvt_f32_f16_e32 v38, v42
	v_cvt_f32_f16_sdwa v39, v42 dst_sel:DWORD dst_unused:UNUSED_PAD src0_sel:WORD_1
	v_cvt_f32_f16_e32 v42, v37
	v_cvt_f32_f16_sdwa v43, v37 dst_sel:DWORD dst_unused:UNUSED_PAD src0_sel:WORD_1
	v_cvt_f32_f16_e32 v66, v41
	v_cvt_f32_f16_sdwa v67, v41 dst_sel:DWORD dst_unused:UNUSED_PAD src0_sel:WORD_1
	v_cvt_f32_f16_e32 v68, v36
	v_cvt_f32_f16_sdwa v69, v36 dst_sel:DWORD dst_unused:UNUSED_PAD src0_sel:WORD_1
	v_cvt_f32_f16_e32 v36, v40
	v_cvt_f32_f16_sdwa v37, v40 dst_sel:DWORD dst_unused:UNUSED_PAD src0_sel:WORD_1
	v_cvt_f32_f16_e32 v40, v47
	v_cvt_f32_f16_sdwa v41, v47 dst_sel:DWORD dst_unused:UNUSED_PAD src0_sel:WORD_1
	v_cvt_f32_f16_e32 v70, v51
	v_cvt_f32_f16_sdwa v71, v51 dst_sel:DWORD dst_unused:UNUSED_PAD src0_sel:WORD_1
	v_cvt_f32_f16_e32 v72, v46
	v_cvt_f32_f16_sdwa v73, v46 dst_sel:DWORD dst_unused:UNUSED_PAD src0_sel:WORD_1
	v_cvt_f32_f16_e32 v46, v50
	v_cvt_f32_f16_sdwa v47, v50 dst_sel:DWORD dst_unused:UNUSED_PAD src0_sel:WORD_1
	v_cvt_f32_f16_e32 v50, v45
	v_cvt_f32_f16_sdwa v51, v45 dst_sel:DWORD dst_unused:UNUSED_PAD src0_sel:WORD_1
	v_cvt_f32_f16_e32 v76, v44
	v_cvt_f32_f16_sdwa v77, v44 dst_sel:DWORD dst_unused:UNUSED_PAD src0_sel:WORD_1
	v_cvt_f32_f16_e32 v44, v48
	v_cvt_f32_f16_sdwa v45, v48 dst_sel:DWORD dst_unused:UNUSED_PAD src0_sel:WORD_1
	v_cvt_f32_f16_e32 v74, v49
	v_cvt_f32_f16_sdwa v75, v49 dst_sel:DWORD dst_unused:UNUSED_PAD src0_sel:WORD_1
	v_mul_f32_e32 v48, 0xbfb8aa3b, v52
	v_mul_f32_e32 v49, 0xbfb8aa3b, v53
	v_exp_f32_e32 v92, v48
	v_pk_add_f32 v[44:45], v[76:77], v[44:45]
	v_exp_f32_e32 v93, v49
	v_pk_add_f32 v[48:49], v[50:51], v[74:75]
	v_pk_mul_f32 v[74:75], v[44:45], v[44:45]
	v_pk_add_f32 v[46:47], v[72:73], v[46:47]
	v_pk_mul_f32 v[72:73], v[48:49], v[48:49]
	v_add_f32_e32 v74, v74, v75
	v_add_f32_e32 v72, v72, v74
	v_pk_add_f32 v[40:41], v[40:41], v[70:71]
	v_pk_mul_f32 v[70:71], v[46:47], v[46:47]
	v_add_f32_e32 v74, 1.0, v92
	v_add_f32_e32 v92, v73, v72
	v_add_f32_e32 v70, v70, v92
	v_pk_add_f32 v[36:37], v[68:69], v[36:37]
	v_pk_mul_f32 v[68:69], v[40:41], v[40:41]
	v_add_f32_e32 v70, v71, v70
	v_add_f32_e32 v68, v68, v70
	v_pk_add_f32 v[42:43], v[42:43], v[66:67]
	v_pk_mul_f32 v[66:67], v[36:37], v[36:37]
	v_add_f32_e32 v68, v69, v68
	v_add_f32_e32 v66, v66, v68
	v_pk_add_f32 v[38:39], v[64:65], v[38:39]
	v_pk_mul_f32 v[64:65], v[42:43], v[42:43]
	v_add_f32_e32 v66, v67, v66
	v_add_f32_e32 v64, v64, v66
	v_pk_add_f32 v[32:33], v[32:33], v[62:63]
	v_pk_mul_f32 v[62:63], v[38:39], v[38:39]
	v_add_f32_e32 v64, v65, v64
	v_add_f32_e32 v62, v62, v64
	v_pk_mul_f32 v[50:51], v[32:33], v[32:33]
	v_add_f32_e32 v62, v63, v62
	v_add_f32_e32 v50, v50, v62
	v_add_f32_e32 v50, v51, v50
	ds_bpermute_b32 v51, v24, v50
	v_mul_f32_e32 v78, 0xbfb8aa3b, v54
	v_mul_f32_e32 v79, 0xbfb8aa3b, v55
	v_mul_f32_e32 v80, 0xbfb8aa3b, v30
	v_mul_f32_e32 v81, 0xbfb8aa3b, v31
	s_waitcnt lgkmcnt(0)
; __device__ __forceinline__ float sigmoidf_(float x) { return __builtin_amdgcn_rcpf(1.0f + __builtin_amdgcn_exp2f(x * -1.4426950408889634f)); }
; __device__ __forceinline__ void gla_group_combine(const Frame& F, int l, bool last, int b, int h, int role, int nroles, unsigned* gwd, bool arrive) {
;     ...
;         ss += __shfl_xor(ss, 1); ss += __shfl_xor(ss, 2); ss += __shfl_xor(ss, 4); ss += __shfl_xor(ss, 8);
;         const float rstd = rsqrtf(ss * (1.0f / 256.0f) + 1e-6f);
;         float y[16];
; #pragma unroll
;         for (int e = 0; e < 16; ++e) y[e] = v[e] * rstd * wv[e] * r[e] * sigmoidf_(r[e]);
;         u32x4 w0, w1; w0.x = pk_f16(y[0], y[1]); w0.y = pk_f16(y[2], y[3]); w0.z = pk_f16(y[4], y[5]); w0.w = pk_f16(y[6], y[7]);
;         w1.x = pk_f16(y[8], y[9]); w1.y = pk_f16(y[10], y[11]); w1.z = pk_f16(y[12], y[13]); w1.w = pk_f16(y[14], y[15]);
;         *(u32x4*)gp = w0; *(u32x4*)(gp + 8) = w1;
	v_add_f32_e32 v50, v50, v51
	ds_bpermute_b32 v51, v25, v50
	v_mul_f32_e32 v82, 0xbfb8aa3b, v56
	v_mul_f32_e32 v83, 0xbfb8aa3b, v57
	v_mul_f32_e32 v84, 0xbfb8aa3b, v28
	v_mul_f32_e32 v85, 0xbfb8aa3b, v29
	s_waitcnt lgkmcnt(0)
	v_add_f32_e32 v50, v50, v51
	ds_bpermute_b32 v51, v26, v50
	v_mul_f32_e32 v86, 0xbfb8aa3b, v58
	v_mul_f32_e32 v87, 0xbfb8aa3b, v59
	v_mul_f32_e32 v88, 0xbfb8aa3b, v34
	v_mul_f32_e32 v89, 0xbfb8aa3b, v35
	s_waitcnt lgkmcnt(0)
	v_add_f32_e32 v50, v50, v51
	ds_bpermute_b32 v51, v27, v50
	v_mul_f32_e32 v90, 0xbfb8aa3b, v60
	v_mul_f32_e32 v91, 0xbfb8aa3b, v61
	v_exp_f32_e32 v78, v78
	v_exp_f32_e32 v79, v79
	s_waitcnt lgkmcnt(0)
	v_add_f32_e32 v50, v50, v51
	v_fmamk_f32 v50, v50, 0x3b800000, v235
	v_mul_f32_e32 v51, 0x4b800000, v50
	v_cmp_gt_f32_e32 vcc, s88, v50
	v_exp_f32_e32 v80, v80
	v_exp_f32_e32 v81, v81
	v_cndmask_b32_e32 v50, v50, v51, vcc
	v_exp_f32_e32 v82, v82
	v_exp_f32_e32 v83, v83
	v_exp_f32_e32 v84, v84
	v_exp_f32_e32 v85, v85
	v_exp_f32_e32 v86, v86
	v_exp_f32_e32 v87, v87
	v_exp_f32_e32 v88, v88
	v_exp_f32_e32 v89, v89
	v_exp_f32_e32 v76, v90
	v_exp_f32_e32 v77, v91
	v_rsq_f32_e32 v50, v50
	v_add_f32_e32 v75, 1.0, v93
	v_add_f32_e32 v78, 1.0, v78
	v_add_f32_e32 v79, 1.0, v79
	v_add_f32_e32 v80, 1.0, v80
	v_add_f32_e32 v81, 1.0, v81
	v_add_f32_e32 v82, 1.0, v82
	v_add_f32_e32 v83, 1.0, v83
	v_add_f32_e32 v84, 1.0, v84
	v_add_f32_e32 v85, 1.0, v85
	v_add_f32_e32 v86, 1.0, v86
	v_add_f32_e32 v87, 1.0, v87
	v_add_f32_e32 v88, 1.0, v88
	v_add_f32_e32 v89, 1.0, v89
	v_add_f32_e32 v90, 1.0, v76
	v_add_f32_e32 v91, 1.0, v77
	v_mul_f32_e32 v51, 0x45800000, v50
	v_rcp_f32_e32 v72, v74
	v_rcp_f32_e32 v73, v75
	v_rcp_f32_e32 v74, v78
	v_rcp_f32_e32 v75, v79
	v_rcp_f32_e32 v76, v80
	v_rcp_f32_e32 v77, v81
	v_rcp_f32_e32 v78, v82
	v_rcp_f32_e32 v79, v83
	v_rcp_f32_e32 v80, v84
	v_rcp_f32_e32 v81, v85
	v_rcp_f32_e32 v82, v86
	v_rcp_f32_e32 v83, v87
	v_rcp_f32_e32 v84, v88
	v_rcp_f32_e32 v85, v89
	v_rcp_f32_e32 v86, v90
	v_rcp_f32_e32 v87, v91
	v_cndmask_b32_e32 v50, v50, v51, vcc
	v_pk_mul_f32 v[44:45], v[44:45], v[50:51] op_sel_hi:[1,0]
	v_pk_mul_f32 v[48:49], v[48:49], v[50:51] op_sel_hi:[1,0]
	v_pk_mul_f32 v[46:47], v[46:47], v[50:51] op_sel_hi:[1,0]
	v_pk_mul_f32 v[40:41], v[40:41], v[50:51] op_sel_hi:[1,0]
	v_pk_mul_f32 v[36:37], v[36:37], v[50:51] op_sel_hi:[1,0]
	v_pk_mul_f32 v[42:43], v[42:43], v[50:51] op_sel_hi:[1,0]
	v_pk_mul_f32 v[38:39], v[38:39], v[50:51] op_sel_hi:[1,0]
	v_pk_mul_f32 v[32:33], v[32:33], v[50:51] op_sel_hi:[1,0]
	v_pk_mul_f32 v[44:45], v[14:15], v[44:45]
	v_pk_mul_f32 v[48:49], v[16:17], v[48:49]
	v_pk_mul_f32 v[46:47], v[10:11], v[46:47]
	v_pk_mul_f32 v[40:41], v[12:13], v[40:41]
	v_pk_mul_f32 v[36:37], v[6:7], v[36:37]
	v_pk_mul_f32 v[42:43], v[8:9], v[42:43]
	v_pk_mul_f32 v[38:39], v[2:3], v[38:39]
	v_pk_mul_f32 v[32:33], v[4:5], v[32:33]
	v_pk_mul_f32 v[44:45], v[44:45], v[60:61]
	v_pk_mul_f32 v[34:35], v[48:49], v[34:35]
	v_pk_mul_f32 v[46:47], v[46:47], v[58:59]
	v_pk_mul_f32 v[28:29], v[40:41], v[28:29]
	v_pk_mul_f32 v[36:37], v[36:37], v[56:57]
	v_pk_mul_f32 v[30:31], v[42:43], v[30:31]
	v_pk_mul_f32 v[38:39], v[38:39], v[54:55]
	v_pk_mul_f32 v[32:33], v[32:33], v[52:53]
	v_pk_mul_f32 v[40:41], v[86:87], v[44:45]
	v_pk_mul_f32 v[34:35], v[84:85], v[34:35]
	v_pk_mul_f32 v[42:43], v[82:83], v[46:47]
	v_pk_mul_f32 v[44:45], v[80:81], v[28:29]
	v_pk_mul_f32 v[36:37], v[78:79], v[36:37]
	v_pk_mul_f32 v[46:47], v[76:77], v[30:31]
	v_pk_mul_f32 v[38:39], v[74:75], v[38:39]
	v_pk_mul_f32 v[48:49], v[72:73], v[32:33]
	v_cvt_pk_f16_f32 v176, v40, v41
	v_cvt_pk_f16_f32 v177, v34, v35
	v_cvt_pk_f16_f32 v178, v42, v43
	v_cvt_pk_f16_f32 v179, v44, v45
	v_cvt_pk_f16_f32 v180, v36, v37
	v_cvt_pk_f16_f32 v181, v46, v47
	v_cvt_pk_f16_f32 v182, v38, v39
	v_cvt_pk_f16_f32 v183, v48, v49
	v_mov_b64_e32 v[184:185], v[20:21]
	v_mov_b64_e32 v[186:187], v[22:23]
	s_cbranch_scc0 .Lcomb_g_last
	v_add_u32_e32 v22, s0, v133
	v_mov_b32_e32 v23, s1
	v_mov_b32_e32 v28, s6
	v_cmp_gt_i32_e32 vcc, s36, v22
	v_mov_b64_e32 v[20:21], s[22:23]
	s_addk_i32 s0, 0x100
	v_cndmask_b32_e32 v23, v23, v28, vcc
	v_add_u32_e32 v22, v22, v23
	v_ashrrev_i32_e32 v23, 31, v22
	v_mad_i64_i32 v[20:21], s[2:3], v22, s14, v[20:21]
	v_lshlrev_b64 v[22:23], 10, v[22:23]
	v_lshl_add_u64 v[20:21], s[30:31], 1, v[20:21]
	v_lshl_add_u64 v[22:23], v[22:23], 0, v[18:19]
	v_lshl_add_u64 v[28:29], v[20:21], 0, v[0:1]
	v_lshlrev_b64 v[36:37], 1, v[22:23]
	v_lshl_add_u64 v[20:21], v[28:29], 0, s[34:35]
	v_add_co_u32_e32 v22, vcc, s36, v28
	v_lshl_add_u64 v[44:45], s[52:53], 0, v[36:37]
	v_lshl_add_u64 v[48:49], s[54:55], 0, v[36:37]
	v_addc_co_u32_e32 v23, vcc, 0, v29, vcc
	global_load_dwordx4 v[28:31], v[20:21], off offset:16
	global_load_dwordx4 v[32:35], v[22:23], off offset:3072
	global_load_dwordx4 v[36:39], v[44:45], off offset:16
	global_load_dwordx4 v[40:43], v[48:49], off offset:16
	s_nop 0
	global_load_dwordx4 v[44:47], v[44:45], off
	s_nop 0
	global_load_dwordx4 v[48:51], v[48:49], off
	s_cmp_lt_i32 s0, s38
	global_store_dwordx4 v[186:187], v[176:179], off offset:3072
	global_store_dwordx4 v[184:185], v[180:183], off offset:16
	s_branch .Lcomb_g_loop
.Lcomb_g_last:
	global_store_dwordx4 v[186:187], v[176:179], off offset:3072
	global_store_dwordx4 v[184:185], v[180:183], off offset:16
	s_branch .LBB0_638
